# strategy 9: FFN-in K-loop load segments open with their ds_reads (precomputed A base), back-edge block moved before the loop-back barrier
# baseline (speedup 1.0000x reference)
; #define PG8_STAGE(bufoff, gbase, voff) do { _Pragma("unroll") for (int _i = 0; _i < 2; ++_i) \
;         __builtin_amdgcn_global_load_lds((const unsigned*)((const char*)(gbase) + (voff)[_i]), (LAS unsigned*)(lds + (bufoff) + ldsw + _i * 8192), 16, 0, 0); } while (0)
; #define PG8_WAIT_V(n) asm volatile("s_waitcnt vmcnt(" #n ")" ::: "memory")
; #define PG8_BAR __builtin_amdgcn_s_barrier()
; template <class Epi, class Sched>
; __device__ __forceinline__ void gemm_phase(LAS unsigned char* lds, const Gemm g, const Sched& S, const Epi& E) {
;     ...
;     for (int i = 0; i < 2; ++i) { int R, C; stage_rc(tid * 16 + i * 8192, R, C); const int Rb = Epi::PERM ? ((R & ~31) + perm32(R & 31)) : R;
;         voffA[i] = (unsigned)(R * g.lda + C) * 2u; voffB[i] = (unsigned)(Rb * g.ldb + C) * 2u; }
;     const size_t kstep = (size_t)(BK * 2);
;     const size_t hstepA = (size_t)HALF * g.lda * 2, hstepB = (size_t)HALF * g.ldb * 2;
;     const size_t tstepA = 2 * hstepA, tstepB = 2 * hstepB;
;     const unsigned ldsw = (unsigned)wid * 1024u;
;     const int aoff = lds_byte(wr * 64 + fr, fq * 8), boff = lds_byte(wc * 32 + fr, fq * 8);
;     ...
;     Unit cur, nxt; int ui = 0;
;     if (!S.next(0, cur)) return;
;     f32x4 acc[2][2][4][2];
; #pragma unroll
;     for (int a = 0; a < 2; ++a)
; #pragma unroll
;         for (int b = 0; b < 2; ++b)
; #pragma unroll
;             for (int m = 0; m < 4; ++m)
; #pragma unroll
;                 for (int n = 0; n < 2; ++n) acc[a][b][m][n] = (f32x4){0.f, 0.f, 0.f, 0.f};
;     bf16x8 At[4][2], B0[2][2], B1[2][2];
;     const char* cA = (const char*)g.A + (size_t)cur.pm * tstepA + (size_t)cur.ka * 2; const char* cB = (const char*)g.Bt + (size_t)cur.pn * tstepB;
;     S.a_ready(cur);
;     PG8_STAGE(PG8_SB(0, 0), cB, voffB); PG8_STAGE(PG8_SB(0, 1), cB + hstepB, voffB); PG8_STAGE(PG8_SA(0, 0), cA, voffA); PG8_STAGE(PG8_SA(0, 1), cA + hstepA, voffA);
;     if (wr == 1) PG8_BAR;
;     PG8_WAIT_V(2); PG8_BAR;
;     PG8_STAGE(PG8_SB(1, 0), cB + kstep, voffB); PG8_STAGE(PG8_SA(1, 0), cA + kstep, voffA); PG8_STAGE(PG8_SB(1, 1), cB + hstepB + kstep, voffB);
;     PG8_WAIT_V(6); PG8_BAR;
.LBB0_131:
	s_add_u32 s12, s14, 0xd000000
	s_addc_u32 s13, s15, 0
	s_add_u32 s14, s14, 0x100000
	s_addc_u32 s15, s15, 0
	s_lshl_b32 s18, s18, 5
	s_and_b32 s21, s18, 0x60
	s_add_i32 m0, s46, 0x18000
	v_lshl_add_u64 v[12:13], v[12:13], 0, s[36:37]
	s_lshl_b32 s20, s17, 13
	s_lshl_b32 s22, s21, 7
	s_waitcnt vmcnt(2)
	s_barrier
	global_load_lds_dwordx4 v[12:13], off
	v_lshl_add_u64 v[10:11], v[10:11], 0, s[36:37]
	s_add_i32 m0, s46, 0x1a000
	s_add_i32 s50, s46, 0x8000
	s_add_i32 s51, s46, 0xa000
	global_load_lds_dwordx4 v[10:11], off
	v_lshl_add_u64 v[6:7], v[6:7], 0, s[36:37]
	s_mov_b32 m0, s50
	s_add_u32 s18, s28, 0x80080
	global_load_lds_dwordx4 v[6:7], off
	v_lshl_add_u64 v[6:7], v[8:9], 0, s[36:37]
	s_mov_b32 m0, s51
	s_addc_u32 s19, s29, 0
	global_load_lds_dwordx4 v[6:7], off
	s_add_i32 m0, s46, 0x1c000
	v_lshl_add_u64 v[6:7], s[18:19], 0, v[4:5]
	global_load_lds_dwordx4 v[6:7], off
	v_lshl_add_u64 v[6:7], s[18:19], 0, v[2:3]
	s_add_i32 m0, s46, 0x1e000
	v_readlane_b32 s18, v253, 57
	global_load_lds_dwordx4 v[6:7], off
	v_lshrrev_b32_e32 v7, 1, v14
	v_and_b32_e32 v7, 24, v7
	v_and_b32_e32 v6, 15, v14
	v_lshlrev_b32_e32 v8, 1, v7
	v_lshl_or_b32 v158, s17, 6, v6
	v_lshl_or_b32 v6, v6, 6, v8
	v_lshlrev_b32_e32 v8, 2, v14
	v_and_b32_e32 v8, 32, v8
	v_bitop3_b32 v9, v6, s20, v8 bitop3:0xde
	v_bitop3_b32 v159, v6, s22, v8 bitop3:0xde
	v_add_u32_e32 v248, 0x10000, v159
	v_lshlrev_b32_e32 v6, 15, v19
	v_and_b32_e32 v6, 0xffff0000, v6
	v_or_b32_e32 v160, s21, v7
	v_lshl_add_u32 v6, v18, 12, v6
	v_and_b32_e32 v7, 1, v19
	v_lshl_or_b32 v6, v7, 6, v6
	v_lshl_add_u32 v138, v20, 1, v6
	v_lshlrev_b32_e32 v6, 15, v15
	v_and_b32_e32 v6, 0xffff0000, v6
	s_waitcnt vmcnt(6)
	v_lshl_add_u32 v6, v16, 12, v6
	v_and_b32_e32 v7, 1, v15
	v_readlane_b32 s19, v253, 58
	s_cmpk_lt_u32 s16, 0x100
	v_lshl_or_b32 v6, v7, 6, v6
	s_mov_b32 s53, s18
	v_readlane_b32 s18, v253, 53
	s_cselect_b64 s[16:17], -1, 0
	v_mov_b32_e32 v139, v5
	v_lshl_add_u32 v140, v17, 1, v6
	v_mov_b32_e32 v141, v5
	s_mov_b32 s52, 0
	v_add_u32_e32 v161, 0, v9
	s_mov_b32 s54, s18
	v_cmp_gt_u32_e32 vcc, 0x100, v14
	s_and_saveexec_b64 s[100:101], vcc
	s_cbranch_execz .Lmy_rsfill_done
	v_lshl_add_u32 v162, s54, 8, v14
	v_lshlrev_b32_e32 v162, 5, v162
	global_load_dwordx4 v[164:167], v162, s[14:15]
	global_load_dwordx4 v[168:171], v162, s[14:15] offset:16
	v_lshlrev_b32_e32 v163, 2, v14
	v_add_u32_e32 v163, 0x21800, v163
	s_waitcnt vmcnt(0)
	v_add_f32_e32 v164, v164, v168
	v_add_f32_e32 v165, v165, v169
	v_add_f32_e32 v166, v166, v170
	v_add_f32_e32 v167, v167, v171
	v_add_f32_e32 v164, v165, v164
	v_add_f32_e32 v166, v166, v167
	v_add_f32_e32 v164, v164, v166
	v_fmamk_f32 v164, v164, 0x3a000000, v1
	v_rsq_f32_e32 v164, v164
	s_nop 0
	ds_write_b32 v163, v164
.Lmy_rsfill_done:
	s_or_b64 exec, exec, s[100:101]
	s_mov_b32 s100, s54
	s_waitcnt lgkmcnt(0)
	s_barrier
	v_readlane_b32 s19, v253, 54
	s_branch .LBB0_134
	s_nop 0
	s_nop 0
	s_nop 0
	s_nop 0
	s_nop 0
	s_nop 0
	s_nop 0
	s_nop 0
	s_nop 0
	s_nop 0
	s_nop 0
	s_nop 0
	s_nop 0
	s_nop 0
	s_nop 0
	s_nop 0
	s_nop 0
	s_nop 0
	s_nop 0
	s_nop 0
	s_nop 0
	s_nop 0
	s_nop 0
	s_nop 0
	s_nop 0
	s_nop 0
	s_nop 0
	s_nop 0
	s_nop 0
.LBB0_132:
	s_mov_b64 s[26:27], 0

; #define PG8_STAGE(bufoff, gbase, voff) do { _Pragma("unroll") for (int _i = 0; _i < 2; ++_i) \
;         __builtin_amdgcn_global_load_lds((const unsigned*)((const char*)(gbase) + (voff)[_i]), (LAS unsigned*)(lds + (bufoff) + ldsw + _i * 8192), 16, 0, 0); } while (0)
; #define PG8_LDA(dst, b, h) do { _Pragma("unroll") for (int m = 0; m < 4; ++m) _Pragma("unroll") for (int k = 0; k < 2; ++k) dst[m][k] = *(const LAS bf16x8*)(lds + PG8_SA(b, h) + aoff + m * 2048 + k * 1024); } while (0)
; #define PG8_LDB(dst, b, h) do { _Pragma("unroll") for (int n = 0; n < 2; ++n) _Pragma("unroll") for (int k = 0; k < 2; ++k) dst[n][k] = *(const LAS bf16x8*)(lds + PG8_SB(b, h) + boff + n * 2048 + k * 1024); } while (0)
; #define PG8_WAIT_V(n) asm volatile("s_waitcnt vmcnt(" #n ")" ::: "memory")
; #define PG8_WAIT_L(n) asm volatile("s_waitcnt lgkmcnt(" #n ")" ::: "memory")
; #define PG8_BAR __builtin_amdgcn_s_barrier()
; #define PG8_SCHED __builtin_amdgcn_sched_barrier(0)
; template <class Epi, class Sched>
; __device__ __forceinline__ void gemm_phase(LAS unsigned char* lds, const Gemm g, const Sched& S, const Epi& E) {
;     ...
;         const bool has_next = S.next(ui + 1, nxt);
;         const char* nA = has_next ? (const char*)g.A + (size_t)nxt.pm * tstepA + (size_t)nxt.ka * 2 : cA; const char* nB = has_next ? (const char*)g.Bt + (size_t)nxt.pn * tstepB : cB;
;         for (int t = 0; t < nt; t += 2) {
;             const bool last = (t == nt - 2);
;             const char* a1 = cA + (size_t)(t + 1) * kstep;
;             const char* a2 = last ? nA : cA + (size_t)(t + 2) * kstep; const char* b2 = last ? nB : cB + (size_t)(t + 2) * kstep;
;             const char* a3 = a2 + kstep; const char* b3 = b2 + kstep;
;             if (last && has_next) S.a_ready(nxt);
;             PG8_LDB(B0, 0, 0); PG8_LDB(B1, 0, 1); PG8_SCHED; PG8_LDA(At, 0, 0); PG8_STAGE(PG8_SA(1, 1), a1 + hstepA, voffA);
;             PG8_WAIT_V(8); PG8_WAIT_L(0); PG8_BAR; PG8_MMA(0, 0, At, B0); PG8_MMA(0, 1, At, B1); PG8_BAR; PG8_SCHED;
;     ...
; #pragma unroll
;         for (int a = 0; a < 2; ++a)
; #pragma unroll
;             for (int b = 0; b < 2; ++b)
; #pragma unroll
;                 for (int m = 0; m < 4; ++m)
; #pragma unroll
;                     for (int n = 0; n < 2; ++n) acc[a][b][m][n] = (f32x4){0.f, 0.f, 0.f, 0.f};
.LBB0_136:
	s_ashr_i32 s21, s20, 31
	s_lshl_b64 s[22:23], s[20:21], 20
	s_add_u32 s22, s34, s22
	s_addc_u32 s23, s42, s23
	s_and_b64 s[24:25], s[38:39], exec
	s_cselect_b32 s21, s23, s27
	s_cselect_b32 s55, s22, s26
	s_ashr_i32 s19, s18, 31
	s_lshl_b64 s[24:25], s[18:19], 20
	s_add_u32 s24, s43, s24
	s_addc_u32 s25, s44, s25
	s_and_b64 s[40:41], s[38:39], exec
	s_cselect_b32 s19, s25, s29
	s_cselect_b32 s56, s24, s28
	s_add_u32 s26, s26, 0x80080
	s_addc_u32 s27, s27, 0
	s_add_u32 s57, s28, 0x100
	v_mov_b32_e32 v6, 0
	s_addc_u32 s58, s29, 0
	s_mov_b32 s59, -2
	v_mov_b32_e32 v7, v6
	v_mov_b32_e32 v8, v6
	v_mov_b32_e32 v9, v6
	v_mov_b32_e32 v14, v6
	v_mov_b32_e32 v15, v6
	v_mov_b32_e32 v16, v6
	v_mov_b32_e32 v17, v6
	v_mov_b32_e32 v22, v6
	v_mov_b32_e32 v23, v6
	v_mov_b32_e32 v24, v6
	v_mov_b32_e32 v25, v6
	v_mov_b32_e32 v30, v6
	v_mov_b32_e32 v31, v6
	v_mov_b32_e32 v32, v6
	v_mov_b32_e32 v33, v6
	v_mov_b32_e32 v38, v6
	v_mov_b32_e32 v39, v6
	v_mov_b32_e32 v40, v6
	v_mov_b32_e32 v41, v6
	v_mov_b32_e32 v46, v6
	v_mov_b32_e32 v47, v6
	v_mov_b32_e32 v48, v6
	v_mov_b32_e32 v49, v6
	v_mov_b32_e32 v54, v6
	v_mov_b32_e32 v55, v6
	v_mov_b32_e32 v56, v6
	v_mov_b32_e32 v57, v6
	v_mov_b32_e32 v62, v6
	v_mov_b32_e32 v63, v6
	v_mov_b32_e32 v64, v6
	v_mov_b32_e32 v65, v6
	v_mov_b32_e32 v10, v6
	v_mov_b32_e32 v11, v6
	v_mov_b32_e32 v12, v6
	v_mov_b32_e32 v13, v6
	v_mov_b32_e32 v18, v6
	v_mov_b32_e32 v19, v6
	v_mov_b32_e32 v20, v6
	v_mov_b32_e32 v21, v6
	v_mov_b32_e32 v26, v6
	v_mov_b32_e32 v27, v6
	v_mov_b32_e32 v28, v6
	v_mov_b32_e32 v29, v6
	v_mov_b32_e32 v34, v6
	v_mov_b32_e32 v35, v6
	v_mov_b32_e32 v36, v6
	v_mov_b32_e32 v37, v6
	v_mov_b32_e32 v42, v6
	v_mov_b32_e32 v43, v6
	v_mov_b32_e32 v44, v6
	v_mov_b32_e32 v45, v6
	v_mov_b32_e32 v50, v6
	v_mov_b32_e32 v51, v6
	v_mov_b32_e32 v52, v6
	v_mov_b32_e32 v53, v6
	v_mov_b32_e32 v58, v6
	v_mov_b32_e32 v59, v6
	v_mov_b32_e32 v60, v6
	v_mov_b32_e32 v61, v6
	v_mov_b32_e32 v66, v6
	v_mov_b32_e32 v67, v6
	v_mov_b32_e32 v68, v6
	v_mov_b32_e32 v69, v6
	v_mov_b32_e32 v70, v6
	v_mov_b32_e32 v71, v6
	v_mov_b32_e32 v72, v6
	v_mov_b32_e32 v73, v6
	v_mov_b32_e32 v78, v6
	v_mov_b32_e32 v79, v6
	v_mov_b32_e32 v80, v6
	v_mov_b32_e32 v81, v6
	v_mov_b32_e32 v86, v6
	v_mov_b32_e32 v87, v6
	v_mov_b32_e32 v88, v6
	v_mov_b32_e32 v89, v6
	v_mov_b32_e32 v94, v6
	v_mov_b32_e32 v95, v6
	v_mov_b32_e32 v96, v6
	v_mov_b32_e32 v97, v6
	v_mov_b32_e32 v102, v6
	v_mov_b32_e32 v103, v6
	v_mov_b32_e32 v104, v6
	v_mov_b32_e32 v105, v6
	v_mov_b32_e32 v110, v6
	v_mov_b32_e32 v111, v6
	v_mov_b32_e32 v112, v6
	v_mov_b32_e32 v113, v6
	v_mov_b32_e32 v118, v6
	v_mov_b32_e32 v119, v6
	v_mov_b32_e32 v120, v6
	v_mov_b32_e32 v121, v6
	v_mov_b32_e32 v126, v6
	v_mov_b32_e32 v127, v6
	v_mov_b32_e32 v128, v6
	v_mov_b32_e32 v129, v6
	v_mov_b32_e32 v74, v6
	v_mov_b32_e32 v75, v6
	v_mov_b32_e32 v76, v6
	v_mov_b32_e32 v77, v6
	v_mov_b32_e32 v82, v6
	v_mov_b32_e32 v83, v6
	v_mov_b32_e32 v84, v6
	v_mov_b32_e32 v85, v6
	v_mov_b32_e32 v90, v6
	v_mov_b32_e32 v91, v6
	v_mov_b32_e32 v92, v6
	v_mov_b32_e32 v93, v6
	v_mov_b32_e32 v98, v6
	v_mov_b32_e32 v99, v6
	v_mov_b32_e32 v100, v6
	v_mov_b32_e32 v101, v6
	v_mov_b32_e32 v106, v6
	v_mov_b32_e32 v107, v6
	v_mov_b32_e32 v108, v6
	v_mov_b32_e32 v109, v6
	v_mov_b32_e32 v114, v6
	v_mov_b32_e32 v115, v6
	v_mov_b32_e32 v116, v6
	v_mov_b32_e32 v117, v6
	v_mov_b32_e32 v122, v6
	v_mov_b32_e32 v123, v6
	v_mov_b32_e32 v124, v6
	v_mov_b32_e32 v125, v6
	v_mov_b32_e32 v130, v6
	v_mov_b32_e32 v131, v6
	v_mov_b32_e32 v132, v6
	v_mov_b32_e32 v133, v6
	s_branch .LBB0_137
.Lmy_k1_head:
	s_barrier
.LBB0_137:
	ds_read_b128 v[142:145], v248
	ds_read_b128 v[146:149], v248 offset:1024
	ds_read_b128 v[150:153], v248 offset:2048
	ds_read_b128 v[154:157], v248 offset:3072
	ds_read_b128 v[162:165], v248 offset:16384
	ds_read_b128 v[166:169], v248 offset:17408
	ds_read_b128 v[170:173], v248 offset:18432
	ds_read_b128 v[174:177], v248 offset:19456
	ds_read_b128 v[178:181], v161
	ds_read_b128 v[182:185], v161 offset:1024
	ds_read_b128 v[186:189], v161 offset:2048
	ds_read_b128 v[190:193], v161 offset:3072
	ds_read_b128 v[194:197], v161 offset:4096
	ds_read_b128 v[212:215], v161 offset:5120
	ds_read_b128 v[216:219], v161 offset:6144
	ds_read_b128 v[220:223], v161 offset:7168
	s_add_u32 s28, s26, 0xfff80080
	s_addc_u32 s29, s27, -1
	s_add_i32 s60, 0, 0x10000
	s_cmp_eq_u32 s59, 28
	s_cselect_b32 s41, s21, s29
	s_cselect_b32 s40, s55, s28
	s_cselect_b32 s29, s19, s58
	s_cselect_b32 s28, s56, s57
	s_add_i32 s62, 0, 0x14000
	s_add_i32 m0, s46, 0xc000
	v_lshl_add_u64 v[224:225], s[26:27], 0, v[138:139]
	global_load_lds_dwordx4 v[224:225], off
	v_lshl_add_u64 v[224:225], s[26:27], 0, v[140:141]
	s_add_i32 m0, s46, 0xe000
	s_nop 0
	global_load_lds_dwordx4 v[224:225], off
	s_waitcnt vmcnt(8)
	s_waitcnt lgkmcnt(0)
	s_barrier
; #define PG8_STAGE(bufoff, gbase, voff) do { _Pragma("unroll") for (int _i = 0; _i < 2; ++_i) \
;         __builtin_amdgcn_global_load_lds((const unsigned*)((const char*)(gbase) + (voff)[_i]), (LAS unsigned*)(lds + (bufoff) + ldsw + _i * 8192), 16, 0, 0); } while (0)
; #define PG8_LDA(dst, b, h) do { _Pragma("unroll") for (int m = 0; m < 4; ++m) _Pragma("unroll") for (int k = 0; k < 2; ++k) dst[m][k] = *(const LAS bf16x8*)(lds + PG8_SA(b, h) + aoff + m * 2048 + k * 1024); } while (0)
; #define PG8_MMA(ai, bj, At, Bt) do { __builtin_amdgcn_s_setprio(1); _Pragma("unroll") for (int m = 0; m < 4; ++m) _Pragma("unroll") for (int n = 0; n < 2; ++n) _Pragma("unroll") for (int k = 0; k < 2; ++k) \
;         acc[ai][bj][m][n] = __builtin_amdgcn_mfma_f32_16x16x32_bf16(Bt[n][k], At[m][k], acc[ai][bj][m][n], 0, 0, 0); __builtin_amdgcn_s_setprio(0); } while (0)
; #define PG8_WAIT_V(n) asm volatile("s_waitcnt vmcnt(" #n ")" ::: "memory")
; #define PG8_WAIT_L(n) asm volatile("s_waitcnt lgkmcnt(" #n ")" ::: "memory")
; #define PG8_BAR __builtin_amdgcn_s_barrier()
; #define PG8_SCHED __builtin_amdgcn_sched_barrier(0)
; template <class Epi, class Sched>
; __device__ __forceinline__ void gemm_phase(LAS unsigned char* lds, const Gemm g, const Sched& S, const Epi& E) {
;     ...
;             PG8_WAIT_V(8); PG8_WAIT_L(0); PG8_BAR; PG8_MMA(0, 0, At, B0); PG8_MMA(0, 1, At, B1); PG8_BAR; PG8_SCHED;
;             PG8_LDA(At, 0, 1); PG8_STAGE(PG8_SB(0, 0), b2, voffB); PG8_STAGE(PG8_SB(0, 1), b2 + hstepB, voffB); PG8_STAGE(PG8_SA(0, 0), a2, voffA);
;             PG8_WAIT_V(8); PG8_WAIT_L(0); PG8_BAR; PG8_MMA(1, 0, At, B0); PG8_MMA(1, 1, At, B1); PG8_BAR; PG8_SCHED;
	s_waitcnt lgkmcnt(0)
	v_mfma_f32_16x16x32_bf16 v[130:133], v[142:145], v[178:181], v[130:133]
	v_mfma_f32_16x16x32_bf16 v[122:125], v[150:153], v[178:181], v[122:125]
	v_mfma_f32_16x16x32_bf16 v[114:117], v[142:145], v[186:189], v[114:117]
	v_mfma_f32_16x16x32_bf16 v[106:109], v[150:153], v[186:189], v[106:109]
	v_mfma_f32_16x16x32_bf16 v[98:101], v[142:145], v[194:197], v[98:101]
	v_mfma_f32_16x16x32_bf16 v[90:93], v[150:153], v[194:197], v[90:93]
	v_mfma_f32_16x16x32_bf16 v[82:85], v[142:145], v[216:219], v[82:85]
	v_mfma_f32_16x16x32_bf16 v[74:77], v[150:153], v[216:219], v[74:77]
	v_mfma_f32_16x16x32_bf16 v[130:133], v[146:149], v[182:185], v[130:133]
	v_mfma_f32_16x16x32_bf16 v[122:125], v[154:157], v[182:185], v[122:125]
	v_mfma_f32_16x16x32_bf16 v[114:117], v[146:149], v[190:193], v[114:117]
	v_mfma_f32_16x16x32_bf16 v[106:109], v[154:157], v[190:193], v[106:109]
	v_mfma_f32_16x16x32_bf16 v[98:101], v[146:149], v[212:215], v[98:101]
	v_mfma_f32_16x16x32_bf16 v[90:93], v[154:157], v[212:215], v[90:93]
	v_mfma_f32_16x16x32_bf16 v[82:85], v[146:149], v[220:223], v[82:85]
	v_mfma_f32_16x16x32_bf16 v[74:77], v[154:157], v[220:223], v[74:77]
	v_mfma_f32_16x16x32_bf16 v[126:129], v[162:165], v[178:181], v[126:129]
	v_mfma_f32_16x16x32_bf16 v[118:121], v[170:173], v[178:181], v[118:121]
	v_mfma_f32_16x16x32_bf16 v[110:113], v[162:165], v[186:189], v[110:113]
	v_mfma_f32_16x16x32_bf16 v[102:105], v[170:173], v[186:189], v[102:105]
	v_mfma_f32_16x16x32_bf16 v[94:97], v[162:165], v[194:197], v[94:97]
	v_mfma_f32_16x16x32_bf16 v[86:89], v[170:173], v[194:197], v[86:89]
	v_mfma_f32_16x16x32_bf16 v[78:81], v[162:165], v[216:219], v[78:81]
	v_mfma_f32_16x16x32_bf16 v[70:73], v[170:173], v[216:219], v[70:73]
	v_mfma_f32_16x16x32_bf16 v[126:129], v[166:169], v[182:185], v[126:129]
	v_mfma_f32_16x16x32_bf16 v[118:121], v[174:177], v[182:185], v[118:121]
	v_mfma_f32_16x16x32_bf16 v[110:113], v[166:169], v[190:193], v[110:113]
	v_mfma_f32_16x16x32_bf16 v[102:105], v[174:177], v[190:193], v[102:105]
	v_mfma_f32_16x16x32_bf16 v[94:97], v[166:169], v[212:215], v[94:97]
	v_mfma_f32_16x16x32_bf16 v[86:89], v[174:177], v[212:215], v[86:89]
	v_mfma_f32_16x16x32_bf16 v[78:81], v[166:169], v[220:223], v[78:81]
	v_mfma_f32_16x16x32_bf16 v[70:73], v[174:177], v[220:223], v[70:73]
	s_barrier
	ds_read_b128 v[178:181], v161 offset:16384
	ds_read_b128 v[182:185], v161 offset:17408
	ds_read_b128 v[186:189], v161 offset:18432
	ds_read_b128 v[190:193], v161 offset:19456
	ds_read_b128 v[194:197], v161 offset:20480
	ds_read_b128 v[212:215], v161 offset:21504
	ds_read_b128 v[216:219], v161 offset:22528
	ds_read_b128 v[220:223], v161 offset:23552
	s_add_i32 s60, s60, s45
	s_mov_b32 m0, s60
	v_lshl_add_u64 v[224:225], s[28:29], 0, v[4:5]
	global_load_lds_dwordx4 v[224:225], off
	s_add_i32 m0, s60, 0x2000
	s_add_u32 s60, s28, 0x80000
	v_lshl_add_u64 v[226:227], s[28:29], 0, v[2:3]
	s_addc_u32 s61, s29, 0
	s_add_i32 s62, s62, s45
	global_load_lds_dwordx4 v[226:227], off
	v_lshl_add_u64 v[228:229], s[60:61], 0, v[4:5]
	s_mov_b32 m0, s62
	v_lshl_add_u64 v[230:231], s[40:41], 0, v[134:135]
	global_load_lds_dwordx4 v[228:229], off
	v_lshl_add_u64 v[228:229], s[60:61], 0, v[2:3]
	s_add_i32 m0, s62, 0x2000
	s_nop 0
	global_load_lds_dwordx4 v[228:229], off
	v_lshl_add_u64 v[228:229], s[40:41], 0, v[136:137]
	s_mov_b32 m0, s46
	s_nop 0
	global_load_lds_dwordx4 v[228:229], off
	s_mov_b32 m0, s47
	s_nop 0
	global_load_lds_dwordx4 v[230:231], off
	s_waitcnt vmcnt(8)
	s_waitcnt lgkmcnt(0)
	s_barrier
	s_waitcnt lgkmcnt(0)
	v_mfma_f32_16x16x32_bf16 v[66:69], v[142:145], v[178:181], v[66:69]
	v_mfma_f32_16x16x32_bf16 v[58:61], v[150:153], v[178:181], v[58:61]
	v_mfma_f32_16x16x32_bf16 v[50:53], v[142:145], v[186:189], v[50:53]
	v_mfma_f32_16x16x32_bf16 v[42:45], v[150:153], v[186:189], v[42:45]
	v_mfma_f32_16x16x32_bf16 v[34:37], v[142:145], v[194:197], v[34:37]
	v_mfma_f32_16x16x32_bf16 v[26:29], v[150:153], v[194:197], v[26:29]
	v_mfma_f32_16x16x32_bf16 v[18:21], v[142:145], v[216:219], v[18:21]
	v_mfma_f32_16x16x32_bf16 v[10:13], v[150:153], v[216:219], v[10:13]
	v_mfma_f32_16x16x32_bf16 v[66:69], v[146:149], v[182:185], v[66:69]
	v_mfma_f32_16x16x32_bf16 v[58:61], v[154:157], v[182:185], v[58:61]
	v_mfma_f32_16x16x32_bf16 v[50:53], v[146:149], v[190:193], v[50:53]
	v_mfma_f32_16x16x32_bf16 v[42:45], v[154:157], v[190:193], v[42:45]
	v_mfma_f32_16x16x32_bf16 v[34:37], v[146:149], v[212:215], v[34:37]
	v_mfma_f32_16x16x32_bf16 v[26:29], v[154:157], v[212:215], v[26:29]
	v_mfma_f32_16x16x32_bf16 v[18:21], v[146:149], v[220:223], v[18:21]
	v_mfma_f32_16x16x32_bf16 v[10:13], v[154:157], v[220:223], v[10:13]
	v_mfma_f32_16x16x32_bf16 v[62:65], v[162:165], v[178:181], v[62:65]
	v_mfma_f32_16x16x32_bf16 v[54:57], v[170:173], v[178:181], v[54:57]
	v_mfma_f32_16x16x32_bf16 v[46:49], v[162:165], v[186:189], v[46:49]
	v_mfma_f32_16x16x32_bf16 v[38:41], v[170:173], v[186:189], v[38:41]
	v_mfma_f32_16x16x32_bf16 v[30:33], v[162:165], v[194:197], v[30:33]
	v_mfma_f32_16x16x32_bf16 v[22:25], v[170:173], v[194:197], v[22:25]
	v_mfma_f32_16x16x32_bf16 v[14:17], v[162:165], v[216:219], v[14:17]
	v_mfma_f32_16x16x32_bf16 v[6:9], v[170:173], v[216:219], v[6:9]
	v_mfma_f32_16x16x32_bf16 v[62:65], v[166:169], v[182:185], v[62:65]
	v_mfma_f32_16x16x32_bf16 v[54:57], v[174:177], v[182:185], v[54:57]
	v_mfma_f32_16x16x32_bf16 v[46:49], v[166:169], v[190:193], v[46:49]
	v_mfma_f32_16x16x32_bf16 v[38:41], v[174:177], v[190:193], v[38:41]
	v_mfma_f32_16x16x32_bf16 v[30:33], v[166:169], v[212:215], v[30:33]
	v_mfma_f32_16x16x32_bf16 v[22:25], v[174:177], v[212:215], v[22:25]
	v_mfma_f32_16x16x32_bf16 v[14:17], v[166:169], v[220:223], v[14:17]
	v_mfma_f32_16x16x32_bf16 v[6:9], v[174:177], v[220:223], v[6:9]
	s_barrier
; #define PG8_STAGE(bufoff, gbase, voff) do { _Pragma("unroll") for (int _i = 0; _i < 2; ++_i) \
;         __builtin_amdgcn_global_load_lds((const unsigned*)((const char*)(gbase) + (voff)[_i]), (LAS unsigned*)(lds + (bufoff) + ldsw + _i * 8192), 16, 0, 0); } while (0)
; #define PG8_LDA(dst, b, h) do { _Pragma("unroll") for (int m = 0; m < 4; ++m) _Pragma("unroll") for (int k = 0; k < 2; ++k) dst[m][k] = *(const LAS bf16x8*)(lds + PG8_SA(b, h) + aoff + m * 2048 + k * 1024); } while (0)
; #define PG8_LDB(dst, b, h) do { _Pragma("unroll") for (int n = 0; n < 2; ++n) _Pragma("unroll") for (int k = 0; k < 2; ++k) dst[n][k] = *(const LAS bf16x8*)(lds + PG8_SB(b, h) + boff + n * 2048 + k * 1024); } while (0)
; #define PG8_MMA(ai, bj, At, Bt) do { __builtin_amdgcn_s_setprio(1); _Pragma("unroll") for (int m = 0; m < 4; ++m) _Pragma("unroll") for (int n = 0; n < 2; ++n) _Pragma("unroll") for (int k = 0; k < 2; ++k) \
;         acc[ai][bj][m][n] = __builtin_amdgcn_mfma_f32_16x16x32_bf16(Bt[n][k], At[m][k], acc[ai][bj][m][n], 0, 0, 0); __builtin_amdgcn_s_setprio(0); } while (0)
; #define PG8_WAIT_V(n) asm volatile("s_waitcnt vmcnt(" #n ")" ::: "memory")
; #define PG8_WAIT_L(n) asm volatile("s_waitcnt lgkmcnt(" #n ")" ::: "memory")
; #define PG8_BAR __builtin_amdgcn_s_barrier()
; #define PG8_SCHED __builtin_amdgcn_sched_barrier(0)
; template <class Epi, class Sched>
; __device__ __forceinline__ void gemm_phase(LAS unsigned char* lds, const Gemm g, const Sched& S, const Epi& E) {
;     ...
;             PG8_LDB(B0, 1, 0); PG8_LDB(B1, 1, 1); PG8_SCHED; PG8_LDA(At, 1, 0); PG8_STAGE(PG8_SA(0, 1), a2 + hstepA, voffA);
;             PG8_WAIT_V(8); PG8_WAIT_L(0); PG8_BAR; PG8_MMA(0, 0, At, B0); PG8_MMA(0, 1, At, B1); PG8_BAR; PG8_SCHED;
	ds_read_b128 v[142:145], v248 offset:32768
	ds_read_b128 v[146:149], v248 offset:33792
	ds_read_b128 v[150:153], v248 offset:34816
	ds_read_b128 v[154:157], v248 offset:35840
	ds_read_b128 v[162:165], v248 offset:49152
	ds_read_b128 v[166:169], v248 offset:50176
	ds_read_b128 v[170:173], v248 offset:51200
	ds_read_b128 v[174:177], v248 offset:52224
	ds_read_b128 v[178:181], v161 offset:32768
	ds_read_b128 v[182:185], v161 offset:33792
	ds_read_b128 v[186:189], v161 offset:34816
	ds_read_b128 v[190:193], v161 offset:35840
	ds_read_b128 v[194:197], v161 offset:36864
	ds_read_b128 v[212:215], v161 offset:37888
	ds_read_b128 v[216:219], v161 offset:38912
	ds_read_b128 v[220:223], v161 offset:39936
	s_add_i32 s60, 0, 0x18000
	s_add_i32 s61, 0, 0x1c000
	s_add_u32 s40, s40, 0x80000
	s_addc_u32 s41, s41, 0
	s_mov_b32 m0, s48
	v_lshl_add_u64 v[236:237], s[40:41], 0, v[136:137]
	global_load_lds_dwordx4 v[236:237], off
	v_lshl_add_u64 v[236:237], s[40:41], 0, v[134:135]
	s_mov_b32 m0, s49
	s_nop 0
	global_load_lds_dwordx4 v[236:237], off
	s_waitcnt vmcnt(8)
	s_waitcnt lgkmcnt(0)
	s_barrier
	s_waitcnt lgkmcnt(0)
	v_mfma_f32_16x16x32_bf16 v[130:133], v[142:145], v[178:181], v[130:133]
	v_mfma_f32_16x16x32_bf16 v[122:125], v[150:153], v[178:181], v[122:125]
	v_mfma_f32_16x16x32_bf16 v[114:117], v[142:145], v[186:189], v[114:117]
	v_mfma_f32_16x16x32_bf16 v[106:109], v[150:153], v[186:189], v[106:109]
	v_mfma_f32_16x16x32_bf16 v[98:101], v[142:145], v[194:197], v[98:101]
	v_mfma_f32_16x16x32_bf16 v[90:93], v[150:153], v[194:197], v[90:93]
	v_mfma_f32_16x16x32_bf16 v[82:85], v[142:145], v[216:219], v[82:85]
	v_mfma_f32_16x16x32_bf16 v[74:77], v[150:153], v[216:219], v[74:77]
	v_mfma_f32_16x16x32_bf16 v[130:133], v[146:149], v[182:185], v[130:133]
	v_mfma_f32_16x16x32_bf16 v[122:125], v[154:157], v[182:185], v[122:125]
	v_mfma_f32_16x16x32_bf16 v[114:117], v[146:149], v[190:193], v[114:117]
	v_mfma_f32_16x16x32_bf16 v[106:109], v[154:157], v[190:193], v[106:109]
	v_mfma_f32_16x16x32_bf16 v[98:101], v[146:149], v[212:215], v[98:101]
	v_mfma_f32_16x16x32_bf16 v[90:93], v[154:157], v[212:215], v[90:93]
	v_mfma_f32_16x16x32_bf16 v[82:85], v[146:149], v[220:223], v[82:85]
	v_mfma_f32_16x16x32_bf16 v[74:77], v[154:157], v[220:223], v[74:77]
	v_mfma_f32_16x16x32_bf16 v[126:129], v[162:165], v[178:181], v[126:129]
	v_mfma_f32_16x16x32_bf16 v[118:121], v[170:173], v[178:181], v[118:121]
	v_mfma_f32_16x16x32_bf16 v[110:113], v[162:165], v[186:189], v[110:113]
	v_mfma_f32_16x16x32_bf16 v[102:105], v[170:173], v[186:189], v[102:105]
	v_mfma_f32_16x16x32_bf16 v[94:97], v[162:165], v[194:197], v[94:97]
	v_mfma_f32_16x16x32_bf16 v[86:89], v[170:173], v[194:197], v[86:89]
	v_mfma_f32_16x16x32_bf16 v[78:81], v[162:165], v[216:219], v[78:81]
	v_mfma_f32_16x16x32_bf16 v[70:73], v[170:173], v[216:219], v[70:73]
	v_mfma_f32_16x16x32_bf16 v[126:129], v[166:169], v[182:185], v[126:129]
	v_mfma_f32_16x16x32_bf16 v[118:121], v[174:177], v[182:185], v[118:121]
	v_mfma_f32_16x16x32_bf16 v[110:113], v[166:169], v[190:193], v[110:113]
	v_mfma_f32_16x16x32_bf16 v[102:105], v[174:177], v[190:193], v[102:105]
	v_mfma_f32_16x16x32_bf16 v[94:97], v[166:169], v[212:215], v[94:97]
	v_mfma_f32_16x16x32_bf16 v[86:89], v[174:177], v[212:215], v[86:89]
	v_mfma_f32_16x16x32_bf16 v[78:81], v[166:169], v[220:223], v[78:81]
	v_mfma_f32_16x16x32_bf16 v[70:73], v[174:177], v[220:223], v[70:73]
	s_barrier
; #define PG8_STAGE(bufoff, gbase, voff) do { _Pragma("unroll") for (int _i = 0; _i < 2; ++_i) \
;         __builtin_amdgcn_global_load_lds((const unsigned*)((const char*)(gbase) + (voff)[_i]), (LAS unsigned*)(lds + (bufoff) + ldsw + _i * 8192), 16, 0, 0); } while (0)
; #define PG8_LDA(dst, b, h) do { _Pragma("unroll") for (int m = 0; m < 4; ++m) _Pragma("unroll") for (int k = 0; k < 2; ++k) dst[m][k] = *(const LAS bf16x8*)(lds + PG8_SA(b, h) + aoff + m * 2048 + k * 1024); } while (0)
; #define PG8_MMA(ai, bj, At, Bt) do { __builtin_amdgcn_s_setprio(1); _Pragma("unroll") for (int m = 0; m < 4; ++m) _Pragma("unroll") for (int n = 0; n < 2; ++n) _Pragma("unroll") for (int k = 0; k < 2; ++k) \
;         acc[ai][bj][m][n] = __builtin_amdgcn_mfma_f32_16x16x32_bf16(Bt[n][k], At[m][k], acc[ai][bj][m][n], 0, 0, 0); __builtin_amdgcn_s_setprio(0); } while (0)
; #define PG8_WAIT_V(n) asm volatile("s_waitcnt vmcnt(" #n ")" ::: "memory")
; #define PG8_WAIT_L(n) asm volatile("s_waitcnt lgkmcnt(" #n ")" ::: "memory")
; #define PG8_BAR __builtin_amdgcn_s_barrier()
; #define PG8_SCHED __builtin_amdgcn_sched_barrier(0)
; template <class Epi, class Sched>
; __device__ __forceinline__ void gemm_phase(LAS unsigned char* lds, const Gemm g, const Sched& S, const Epi& E) {
;     ...
;             PG8_LDA(At, 1, 1); PG8_STAGE(PG8_SB(1, 0), b3, voffB); PG8_STAGE(PG8_SB(1, 1), b3 + hstepB, voffB); PG8_STAGE(PG8_SA(1, 0), a3, voffA);
;             PG8_WAIT_V(8); PG8_WAIT_L(0); PG8_BAR; PG8_MMA(1, 0, At, B0); PG8_MMA(1, 1, At, B1); PG8_BAR; PG8_SCHED;
;         }
	ds_read_b128 v[178:181], v161 offset:49152
	ds_read_b128 v[182:185], v161 offset:50176
	ds_read_b128 v[186:189], v161 offset:51200
	ds_read_b128 v[190:193], v161 offset:52224
	ds_read_b128 v[194:197], v161 offset:53248
	ds_read_b128 v[212:215], v161 offset:54272
	ds_read_b128 v[216:219], v161 offset:55296
	ds_read_b128 v[220:223], v161 offset:56320
	s_add_i32 s40, s60, s45
	s_mov_b32 m0, s40
	v_lshl_add_u64 v[224:225], v[224:225], 0, s[36:37]
	global_load_lds_dwordx4 v[224:225], off
	s_add_i32 m0, s40, 0x2000
	s_add_u32 s28, s28, 0x80080
	v_lshl_add_u64 v[224:225], v[226:227], 0, s[36:37]
	s_addc_u32 s29, s29, 0
	s_add_i32 s40, s61, s45
	global_load_lds_dwordx4 v[224:225], off
	v_lshl_add_u64 v[224:225], s[28:29], 0, v[4:5]
	s_mov_b32 m0, s40
	s_nop 0
	global_load_lds_dwordx4 v[224:225], off
	v_lshl_add_u64 v[224:225], s[28:29], 0, v[2:3]
	s_add_i32 m0, s40, 0x2000
	s_nop 0
	global_load_lds_dwordx4 v[224:225], off
	v_lshl_add_u64 v[224:225], v[228:229], 0, s[36:37]
	s_mov_b32 m0, s50
	s_nop 0
	global_load_lds_dwordx4 v[224:225], off
	v_lshl_add_u64 v[224:225], v[230:231], 0, s[36:37]
	s_mov_b32 m0, s51
	s_nop 0
	global_load_lds_dwordx4 v[224:225], off
	s_waitcnt vmcnt(8)
	s_waitcnt lgkmcnt(0)
	s_barrier
	s_waitcnt lgkmcnt(0)
	v_mfma_f32_16x16x32_bf16 v[66:69], v[142:145], v[178:181], v[66:69]
	v_mfma_f32_16x16x32_bf16 v[58:61], v[150:153], v[178:181], v[58:61]
	v_mfma_f32_16x16x32_bf16 v[50:53], v[142:145], v[186:189], v[50:53]
	v_mfma_f32_16x16x32_bf16 v[42:45], v[150:153], v[186:189], v[42:45]
	v_mfma_f32_16x16x32_bf16 v[34:37], v[142:145], v[194:197], v[34:37]
	v_mfma_f32_16x16x32_bf16 v[26:29], v[150:153], v[194:197], v[26:29]
	v_mfma_f32_16x16x32_bf16 v[18:21], v[142:145], v[216:219], v[18:21]
	v_mfma_f32_16x16x32_bf16 v[10:13], v[150:153], v[216:219], v[10:13]
	v_mfma_f32_16x16x32_bf16 v[66:69], v[146:149], v[182:185], v[66:69]
	v_mfma_f32_16x16x32_bf16 v[58:61], v[154:157], v[182:185], v[58:61]
	v_mfma_f32_16x16x32_bf16 v[50:53], v[146:149], v[190:193], v[50:53]
	v_mfma_f32_16x16x32_bf16 v[42:45], v[154:157], v[190:193], v[42:45]
	v_mfma_f32_16x16x32_bf16 v[34:37], v[146:149], v[212:215], v[34:37]
	v_mfma_f32_16x16x32_bf16 v[26:29], v[154:157], v[212:215], v[26:29]
	v_mfma_f32_16x16x32_bf16 v[18:21], v[146:149], v[220:223], v[18:21]
	v_mfma_f32_16x16x32_bf16 v[10:13], v[154:157], v[220:223], v[10:13]
	v_mfma_f32_16x16x32_bf16 v[62:65], v[162:165], v[178:181], v[62:65]
	v_mfma_f32_16x16x32_bf16 v[54:57], v[170:173], v[178:181], v[54:57]
	v_mfma_f32_16x16x32_bf16 v[46:49], v[162:165], v[186:189], v[46:49]
	v_mfma_f32_16x16x32_bf16 v[38:41], v[170:173], v[186:189], v[38:41]
	v_mfma_f32_16x16x32_bf16 v[30:33], v[162:165], v[194:197], v[30:33]
	v_mfma_f32_16x16x32_bf16 v[22:25], v[170:173], v[194:197], v[22:25]
	v_mfma_f32_16x16x32_bf16 v[14:17], v[162:165], v[216:219], v[14:17]
	v_mfma_f32_16x16x32_bf16 v[6:9], v[170:173], v[216:219], v[6:9]
	v_mfma_f32_16x16x32_bf16 v[62:65], v[166:169], v[182:185], v[62:65]
	v_mfma_f32_16x16x32_bf16 v[54:57], v[174:177], v[182:185], v[54:57]
	v_mfma_f32_16x16x32_bf16 v[46:49], v[166:169], v[190:193], v[46:49]
	v_mfma_f32_16x16x32_bf16 v[38:41], v[174:177], v[190:193], v[38:41]
	v_mfma_f32_16x16x32_bf16 v[30:33], v[166:169], v[212:215], v[30:33]
	v_mfma_f32_16x16x32_bf16 v[22:25], v[174:177], v[212:215], v[22:25]
	v_mfma_f32_16x16x32_bf16 v[14:17], v[166:169], v[220:223], v[14:17]
	v_mfma_f32_16x16x32_bf16 v[6:9], v[174:177], v[220:223], v[6:9]
	s_add_i32 s59, s59, 2
	s_add_u32 s26, s26, 0x100
	s_addc_u32 s27, s27, 0
	s_add_u32 s57, s57, 0x100
	s_addc_u32 s58, s58, 0
	s_cmp_gt_u32 s59, 29
	s_cbranch_scc0 .Lmy_k1_head
	s_barrier
	s_and_b64 vcc, exec, s[16:17]
	s_cbranch_vccz .LBB0_140
	s_barrier

; #define PG8_STAGE(bufoff, gbase, voff) do { _Pragma("unroll") for (int _i = 0; _i < 2; ++_i) \
;         __builtin_amdgcn_global_load_lds((const unsigned*)((const char*)(gbase) + (voff)[_i]), (LAS unsigned*)(lds + (bufoff) + ldsw + _i * 8192), 16, 0, 0); } while (0)
; #define PG8_WAIT_V(n) asm volatile("s_waitcnt vmcnt(" #n ")" ::: "memory")
; #define PG8_BAR __builtin_amdgcn_s_barrier()
; template <class Epi, class Sched>
; __device__ __forceinline__ void gemm_phase(LAS unsigned char* lds, const Gemm g, const Sched& S, const Epi& E) {
;     ...
;     f32x4 acc[2][2][4][2];
; #pragma unroll
;     for (int a = 0; a < 2; ++a)
; #pragma unroll
;         for (int b = 0; b < 2; ++b)
; #pragma unroll
;             for (int m = 0; m < 4; ++m)
; #pragma unroll
;                 for (int n = 0; n < 2; ++n) acc[a][b][m][n] = (f32x4){0.f, 0.f, 0.f, 0.f};
;     bf16x8 At[4][2], B0[2][2], B1[2][2];
;     const char* cA = (const char*)g.A + (size_t)cur.pm * tstepA + (size_t)cur.ka * 2; const char* cB = (const char*)g.Bt + (size_t)cur.pn * tstepB;
;     S.a_ready(cur);
;     PG8_STAGE(PG8_SB(0, 0), cB, voffB); PG8_STAGE(PG8_SB(0, 1), cB + hstepB, voffB); PG8_STAGE(PG8_SA(0, 0), cA, voffA); PG8_STAGE(PG8_SA(0, 1), cA + hstepA, voffA);
;     if (wr == 1) PG8_BAR;
;     PG8_WAIT_V(2); PG8_BAR;
;     PG8_STAGE(PG8_SB(1, 0), cB + kstep, voffB); PG8_STAGE(PG8_SA(1, 0), cA + kstep, voffA); PG8_STAGE(PG8_SB(1, 1), cB + hstepB + kstep, voffB);
;     PG8_WAIT_V(6); PG8_BAR;
.LBB0_267:
	v_lshl_add_u64 v[14:15], s[24:25], 0, v[4:5]
	v_mov_b32_e32 v3, v5
	v_and_b32_e32 v142, 15, v143
	v_and_b32_e32 v22, 48, v143
	v_lshlrev_b32_e32 v23, 2, v143
	v_lshl_add_u64 v[16:17], s[24:25], 0, v[2:3]
	s_and_b32 s48, s44, 3
	v_lshl_or_b32 v22, v142, 6, v22
	s_lshl_b32 s4, s47, 13
	v_and_b32_e32 v23, 32, v23
	s_add_i32 m0, s50, 0x18000
	v_lshl_add_u64 v[14:15], v[14:15], 0, s[36:37]
	v_lshl_add_u64 v[18:19], s[20:21], 0, v[4:5]
	v_bitop3_b32 v24, v22, s4, v23 bitop3:0xde
	s_lshl_b32 s4, s48, 12
	s_waitcnt vmcnt(2)
	s_barrier
	global_load_lds_dwordx4 v[14:15], off
	v_lshl_add_u64 v[14:15], v[16:17], 0, s[36:37]
	s_add_i32 m0, s50, 0x1a000
	s_add_i32 s54, s50, 0x8000
	s_add_i32 s55, s50, 0xa000
	v_lshl_add_u64 v[20:21], s[20:21], 0, v[2:3]
	v_bitop3_b32 v144, v22, s4, v23 bitop3:0xde
	global_load_lds_dwordx4 v[14:15], off
	v_lshl_add_u64 v[14:15], v[18:19], 0, s[36:37]
	s_mov_b32 m0, s54
	s_add_u32 s4, s24, 0x158080
	global_load_lds_dwordx4 v[14:15], off
	v_lshl_add_u64 v[14:15], v[20:21], 0, s[36:37]
	s_mov_b32 m0, s55
	s_addc_u32 s5, s25, 0
	global_load_lds_dwordx4 v[14:15], off
	s_add_i32 m0, s50, 0x1c000
	v_lshl_add_u64 v[14:15], s[4:5], 0, v[4:5]
	global_load_lds_dwordx4 v[14:15], off
	v_lshl_add_u64 v[14:15], s[4:5], 0, v[2:3]
	s_add_i32 m0, s50, 0x1e000
	s_movk_i32 s10, 0x1580
	global_load_lds_dwordx4 v[14:15], off
	v_lshrrev_b32_e32 v11, 1, v11
	v_mul_lo_u32 v10, v10, s10
	s_mov_b32 s22, 0x15800
	v_mad_u64_u32 v[10:11], s[4:5], v11, s22, v[10:11]
	v_or_b32_e32 v10, v10, v12
	v_add_lshl_u32 v134, v10, v13, 1
	v_lshrrev_b32_e32 v10, 1, v6
	v_mul_lo_u32 v6, v7, s10
	v_mad_u64_u32 v[6:7], s[4:5], v10, s22, v[6:7]
	s_waitcnt vmcnt(6)
	v_or_b32_e32 v6, v6, v8
	s_cmpk_lt_u32 s45, 0x100
	v_add_lshl_u32 v136, v6, v9, 1
	v_mov_b32_e32 v6, 0
	v_readlane_b32 s4, v254, 13
	s_cselect_b64 s[18:19], -1, 0
	v_mov_b32_e32 v135, v5
	v_mov_b32_e32 v137, v5
	s_mov_b32 s59, 0
	v_add_u32_e32 v145, 0, v24
	s_mov_b32 s10, s4
	v_readlane_b32 s46, v253, 61
	v_mov_b32_e32 v7, v6
	v_mov_b32_e32 v8, v6
	v_mov_b32_e32 v9, v6
	v_mov_b32_e32 v10, v6
	v_mov_b32_e32 v11, v6
	v_mov_b32_e32 v12, v6
	v_mov_b32_e32 v13, v6
	v_mov_b32_e32 v14, v6
	v_mov_b32_e32 v15, v6
	v_mov_b32_e32 v16, v6
	v_mov_b32_e32 v17, v6
	v_mov_b32_e32 v18, v6
	v_mov_b32_e32 v19, v6
	v_mov_b32_e32 v20, v6
	v_mov_b32_e32 v21, v6
	v_mov_b32_e32 v22, v6
	v_mov_b32_e32 v23, v6
	v_mov_b32_e32 v24, v6
	v_mov_b32_e32 v25, v6
	v_mov_b32_e32 v30, v6
	v_mov_b32_e32 v31, v6
	v_mov_b32_e32 v32, v6
	v_mov_b32_e32 v33, v6
	v_mov_b32_e32 v38, v6
	v_mov_b32_e32 v39, v6
	v_mov_b32_e32 v40, v6
	v_mov_b32_e32 v41, v6
	v_mov_b32_e32 v46, v6
	v_mov_b32_e32 v47, v6
	v_mov_b32_e32 v48, v6
	v_mov_b32_e32 v49, v6
	v_mov_b32_e32 v26, v6
	v_mov_b32_e32 v27, v6
	v_mov_b32_e32 v28, v6
	v_mov_b32_e32 v29, v6
	v_mov_b32_e32 v34, v6
	v_mov_b32_e32 v35, v6
	v_mov_b32_e32 v36, v6
	v_mov_b32_e32 v37, v6
	v_mov_b32_e32 v42, v6
	v_mov_b32_e32 v43, v6
	v_mov_b32_e32 v44, v6
	v_mov_b32_e32 v45, v6
	v_mov_b32_e32 v50, v6
	v_mov_b32_e32 v51, v6
	v_mov_b32_e32 v52, v6
	v_mov_b32_e32 v53, v6
	v_mov_b32_e32 v54, v6
	v_mov_b32_e32 v55, v6
	v_mov_b32_e32 v56, v6
	v_mov_b32_e32 v57, v6
	v_mov_b32_e32 v58, v6
	v_mov_b32_e32 v59, v6
	v_mov_b32_e32 v60, v6
	v_mov_b32_e32 v61, v6
	v_mov_b32_e32 v62, v6
	v_mov_b32_e32 v63, v6
	v_mov_b32_e32 v64, v6
	v_mov_b32_e32 v65, v6
	v_mov_b32_e32 v66, v6
	v_mov_b32_e32 v67, v6
	v_mov_b32_e32 v68, v6
	v_mov_b32_e32 v69, v6
	v_mov_b32_e32 v70, v6
	v_mov_b32_e32 v71, v6
	v_mov_b32_e32 v72, v6
	v_mov_b32_e32 v73, v6
	v_mov_b32_e32 v74, v6
	v_mov_b32_e32 v75, v6
	v_mov_b32_e32 v76, v6
	v_mov_b32_e32 v77, v6
	v_mov_b32_e32 v78, v6
	v_mov_b32_e32 v79, v6
	v_mov_b32_e32 v80, v6
	v_mov_b32_e32 v81, v6
	v_mov_b32_e32 v82, v6
	v_mov_b32_e32 v83, v6
	v_mov_b32_e32 v84, v6
	v_mov_b32_e32 v85, v6
	v_mov_b32_e32 v86, v6
	v_mov_b32_e32 v87, v6
	v_mov_b32_e32 v88, v6
	v_mov_b32_e32 v89, v6
	v_mov_b32_e32 v94, v6
	v_mov_b32_e32 v95, v6
	v_mov_b32_e32 v96, v6
	v_mov_b32_e32 v97, v6
	v_mov_b32_e32 v102, v6
	v_mov_b32_e32 v103, v6
	v_mov_b32_e32 v104, v6
	v_mov_b32_e32 v105, v6
	v_mov_b32_e32 v114, v6
	v_mov_b32_e32 v115, v6
	v_mov_b32_e32 v116, v6
	v_mov_b32_e32 v117, v6
	v_mov_b32_e32 v90, v6
	v_mov_b32_e32 v91, v6
	v_mov_b32_e32 v92, v6
	v_mov_b32_e32 v93, v6
	v_mov_b32_e32 v98, v6
	v_mov_b32_e32 v99, v6
	v_mov_b32_e32 v100, v6
	v_mov_b32_e32 v101, v6
	v_mov_b32_e32 v106, v6
	v_mov_b32_e32 v107, v6
	v_mov_b32_e32 v108, v6
	v_mov_b32_e32 v109, v6
	v_mov_b32_e32 v110, v6
	v_mov_b32_e32 v111, v6
	v_mov_b32_e32 v112, v6
	v_mov_b32_e32 v113, v6
	v_mov_b32_e32 v118, v6
	v_mov_b32_e32 v119, v6
	v_mov_b32_e32 v120, v6
	v_mov_b32_e32 v121, v6
	v_mov_b32_e32 v122, v6
	v_mov_b32_e32 v123, v6
	v_mov_b32_e32 v124, v6
	v_mov_b32_e32 v125, v6
	v_mov_b32_e32 v126, v6
	v_mov_b32_e32 v127, v6
	v_mov_b32_e32 v128, v6
	v_mov_b32_e32 v129, v6
	v_mov_b32_e32 v130, v6
	v_mov_b32_e32 v131, v6
	v_mov_b32_e32 v132, v6
	v_mov_b32_e32 v133, v6
	s_barrier
	s_branch .LBB0_270
	s_nop 0
	s_nop 0
	s_nop 0
	s_nop 0
	s_nop 0
	s_nop 0
	s_nop 0
	s_nop 0
	s_nop 0
	s_nop 0
	s_nop 0
	s_nop 0
	s_nop 0
	s_nop 0
	s_nop 0
	s_nop 0
	s_nop 0
	s_nop 0
	s_nop 0
	s_nop 0
	s_nop 0
	s_nop 0
	s_nop 0
	s_nop 0
	s_nop 0
	s_nop 0
	s_nop 0
	s_nop 0
	s_nop 0
	s_nop 0
	s_nop 0
	s_nop 0
	s_nop 0
	s_nop 0
	s_nop 0
	s_nop 0
	s_nop 0
	s_nop 0
	s_nop 0
	s_nop 0
	s_nop 0
	s_nop 0
	s_nop 0
	s_nop 0
	s_nop 0
